# scan loop: waves 4-7 keep s_setprio 1 in the other barrier intervals (asymmetry between the two waves of each SIMD)
# speedup vs baseline: 1.0113x; 1.0113x over previous
; __device__ __forceinline__ uint2 pack4(f32x4 v) { uint2 u; u.x = cvt_pk_bf16(v[0], v[1]); u.y = cvt_pk_bf16(v[2], v[3]); return u; }
; #define MFMA16(a, b, c) __builtin_amdgcn_mfma_f32_16x16x32_bf16(a, b, c, 0, 0, 0)
; __device__ __forceinline__ void scan_phase(PREF p, char* smem, const int wid_u) {
;     ...
;       lds_barrier();
;       {
;         const int tt = wave & 1, rt = wave >> 1;
;         const f32x4 zero = {0.f, 0.f, 0.f, 0.f};
;         const bf16x8 tf = ldfrag(TT, 40, tt * 16, 0, fr, fq);
;         const f32x4 zacc = MFMA16(tf, ldfrag(VNb, 40, rt * 16, 0, fr, fq), zero);
;         const f32x4 wacc = MFMA16(tf, ldfrag(AtTb, 40, rt * 16, 0, fr, fq), zero);
;         *(uint2*)(Zb + (rt * 16 + fr) * 40 + tt * 16 + fq * 4) = pack4(zacc);
;         *(uint2*)(Wb + (rt * 16 + fr) * 40 + tt * 16 + fq * 4) = pack4(wacc);
;       }
;       lds_barrier();
.LBB0_587:
	s_setprio 0
	s_cmp_lt_u32 s90, 4
	s_cbranch_scc1 .Lprio_base_skip
	s_setprio 1

; __device__ __forceinline__ void scan_phase(PREF p, char* smem, const int wid_u) {
;     ...
;     {
;       const int ip = (nch - 1) * 32 + hn * 16 + fr, tp = d ? T - 1 - ip : ip;
;       *(uint2*)(yout + (size_t)(r0seq + tp) * 512 + h * 64 + mt * 16 + fq * 4) = y_def;
;     }
.LBB0_603:
	s_setprio 0
	s_add_i32 s4, s92, s84
	s_sub_i32 s4, s4, 32
	s_waitcnt vmcnt(1)
	v_or_b32_e32 v0, s4, v77
	v_xad_u32 v1, v0, -1, s92
	v_cndmask_b32_e64 v0, v1, v0, s[2:3]
	v_add_u32_e32 v0, s91, v0
	v_ashrrev_i32_e32 v1, 31, v0
	v_lshlrev_b64 v[0:1], 10, v[0:1]
	v_lshl_add_u64 v[0:1], s[64:65], 0, v[0:1]
	s_lshl_b32 s2, s89, 1
	s_mov_b32 s3, 0
	v_lshl_add_u64 v[0:1], v[0:1], 0, s[2:3]
	v_lshl_add_u64 v[0:1], s[68:69], 1, v[0:1]
	v_lshlrev_b32_e32 v2, 1, v80
	v_mov_b32_e32 v3, 0
	v_lshl_add_u64 v[0:1], v[0:1], 0, v[2:3]
	global_store_dwordx2 v[0:1], v[92:93], off
	s_load_dword s85, s[0:1], 0x120
	v_readlane_b32 s60, v254, 5
	v_readlane_b32 s54, v254, 0
	v_readlane_b32 s84, v254, 4
	v_readlane_b32 s57, v254, 2
	v_readlane_b32 s58, v254, 3
	v_readlane_b32 s61, v254, 6
	v_readlane_b32 s55, v254, 1
